# SwiGLU epilogues of the FFN gate/up GEMMs (P1, P11): packed-f32 VALU (v_pk_mul/add_f32 on register pairs, same IEEE ops per element), 36 instead of 52 VALU instructions per 8 outputs
# speedup vs baseline: 1.0049x; 1.0034x over previous
; __device__ __forceinline__ unsigned cvt_pk_bf16(float lo, float hi) { unsigned r; asm volatile("v_cvt_pk_bf16_f32 %0, %1, %2" : "=v"(r) : "v"(lo), "v"(hi)); return r; }
; __device__ __forceinline__ float silu_f(float x) { return x * sigmoid_f(x); }
;     __device__ __forceinline__ void operator()(const f32x4 (&acc)[2][2][4][2], const Unit& u, int wr, int wc, int fr, int fq) const {
;         const int row0 = u.pm * BM + wr * 64 + fr; const int col0 = u.pn * HALF + wc * 32 + 8 * fq;
; #pragma unroll
;         for (int ai = 0; ai < 2; ++ai)
; #pragma unroll
;             for (int m = 0; m < 4; ++m) {
;                 bf16_t* rowp = O + (size_t)(row0 + ai * HALF + m * 16) * ldc + col0;
;                 const f32x4 g0 = acc[ai][0][m][0], g1 = acc[ai][0][m][1], u0 = acc[ai][1][m][0], u1 = acc[ai][1][m][1];
;                 u32x4 w;
;                 w.x = cvt_pk_bf16(silu_f(g0[0]) * u0[0], silu_f(g0[1]) * u0[1]); w.y = cvt_pk_bf16(silu_f(g0[2]) * u0[2], silu_f(g0[3]) * u0[3]);
;                 w.z = cvt_pk_bf16(silu_f(g1[0]) * u1[0], silu_f(g1[1]) * u1[1]); w.w = cvt_pk_bf16(silu_f(g1[2]) * u1[2], silu_f(g1[3]) * u1[3]);
;                 *(u32x4*)rowp = w;
;             }
.LBB0_215:
	v_lshl_or_b32 v146, s59, 7, v150
	v_lshl_add_u32 v154, s26, 8, v148
	v_ashrrev_i32_e32 v147, 31, v146
	v_mov_b64_e32 v[144:145], s[12:13]
	v_mad_i64_i32 v[156:157], s[0:1], v154, s58, v[144:145]
	v_lshlrev_b64 v[146:147], 1, v[146:147]
	v_lshl_add_u64 v[156:157], v[156:157], 0, v[146:147]
	s_mov_b32 s98, 0xbfb8aa3b
	s_mov_b32 s100, 1.0
	v_pk_mul_f32 v[234:235], v[124:125], s[98:99] op_sel_hi:[1,0]
	v_pk_mul_f32 v[236:237], v[126:127], s[98:99] op_sel_hi:[1,0]
	v_pk_mul_f32 v[238:239], v[120:121], s[98:99] op_sel_hi:[1,0]
	v_pk_mul_f32 v[240:241], v[122:123], s[98:99] op_sel_hi:[1,0]
	v_exp_f32_e32 v234, v234
	v_exp_f32_e32 v235, v235
	v_exp_f32_e32 v236, v236
	v_exp_f32_e32 v237, v237
	v_exp_f32_e32 v238, v238
	v_exp_f32_e32 v239, v239
	v_exp_f32_e32 v240, v240
	v_exp_f32_e32 v241, v241
	v_pk_add_f32 v[234:235], v[234:235], s[100:101] op_sel_hi:[1,0]
	v_pk_add_f32 v[236:237], v[236:237], s[100:101] op_sel_hi:[1,0]
	v_pk_add_f32 v[238:239], v[238:239], s[100:101] op_sel_hi:[1,0]
	v_pk_add_f32 v[240:241], v[240:241], s[100:101] op_sel_hi:[1,0]
	v_rcp_f32_e32 v234, v234
	v_rcp_f32_e32 v235, v235
	v_rcp_f32_e32 v236, v236
	v_rcp_f32_e32 v237, v237
	v_rcp_f32_e32 v238, v238
	v_rcp_f32_e32 v239, v239
	v_rcp_f32_e32 v240, v240
	v_rcp_f32_e32 v241, v241
	v_pk_mul_f32 v[234:235], v[124:125], v[234:235]
	v_pk_mul_f32 v[236:237], v[126:127], v[236:237]
	v_pk_mul_f32 v[238:239], v[120:121], v[238:239]
	v_pk_mul_f32 v[240:241], v[122:123], v[240:241]
	v_pk_mul_f32 v[234:235], v[234:235], v[116:117]
	v_pk_mul_f32 v[236:237], v[236:237], v[118:119]
	v_pk_mul_f32 v[238:239], v[238:239], v[112:113]
	v_pk_mul_f32 v[240:241], v[240:241], v[114:115]
	v_cvt_pk_bf16_f32 v116, v234, v235
	v_cvt_pk_bf16_f32 v117, v236, v237
	v_cvt_pk_bf16_f32 v118, v238, v239
	v_cvt_pk_bf16_f32 v119, v240, v241
	global_store_dwordx4 v[156:157], v[116:119], off
	v_or_b32_e32 v112, 16, v154
	v_mad_i64_i32 v[112:113], s[0:1], v112, s58, v[144:145]
	v_lshl_add_u64 v[112:113], v[112:113], 0, v[146:147]
	v_pk_mul_f32 v[234:235], v[108:109], s[98:99] op_sel_hi:[1,0]
	v_pk_mul_f32 v[236:237], v[110:111], s[98:99] op_sel_hi:[1,0]
	v_pk_mul_f32 v[238:239], v[104:105], s[98:99] op_sel_hi:[1,0]
	v_pk_mul_f32 v[240:241], v[106:107], s[98:99] op_sel_hi:[1,0]
	v_exp_f32_e32 v234, v234
	v_exp_f32_e32 v235, v235
	v_exp_f32_e32 v236, v236
	v_exp_f32_e32 v237, v237
	v_exp_f32_e32 v238, v238
	v_exp_f32_e32 v239, v239
	v_exp_f32_e32 v240, v240
	v_exp_f32_e32 v241, v241
	v_pk_add_f32 v[234:235], v[234:235], s[100:101] op_sel_hi:[1,0]
	v_pk_add_f32 v[236:237], v[236:237], s[100:101] op_sel_hi:[1,0]
	v_pk_add_f32 v[238:239], v[238:239], s[100:101] op_sel_hi:[1,0]
	v_pk_add_f32 v[240:241], v[240:241], s[100:101] op_sel_hi:[1,0]
	v_rcp_f32_e32 v234, v234
	v_rcp_f32_e32 v235, v235
	v_rcp_f32_e32 v236, v236
	v_rcp_f32_e32 v237, v237
	v_rcp_f32_e32 v238, v238
	v_rcp_f32_e32 v239, v239
	v_rcp_f32_e32 v240, v240
	v_rcp_f32_e32 v241, v241
	v_pk_mul_f32 v[234:235], v[108:109], v[234:235]
	v_pk_mul_f32 v[236:237], v[110:111], v[236:237]
	v_pk_mul_f32 v[238:239], v[104:105], v[238:239]
	v_pk_mul_f32 v[240:241], v[106:107], v[240:241]
	v_pk_mul_f32 v[234:235], v[234:235], v[100:101]
	v_pk_mul_f32 v[236:237], v[236:237], v[102:103]
	v_pk_mul_f32 v[238:239], v[238:239], v[96:97]
	v_pk_mul_f32 v[240:241], v[240:241], v[98:99]
	v_cvt_pk_bf16_f32 v100, v234, v235
	v_cvt_pk_bf16_f32 v101, v236, v237
	v_cvt_pk_bf16_f32 v102, v238, v239
	v_cvt_pk_bf16_f32 v103, v240, v241
	global_store_dwordx4 v[112:113], v[100:103], off
	v_or_b32_e32 v96, 32, v154
	v_mad_i64_i32 v[96:97], s[0:1], v96, s58, v[144:145]
	v_lshl_add_u64 v[96:97], v[96:97], 0, v[146:147]
	v_pk_mul_f32 v[234:235], v[92:93], s[98:99] op_sel_hi:[1,0]
	v_pk_mul_f32 v[236:237], v[94:95], s[98:99] op_sel_hi:[1,0]
	v_pk_mul_f32 v[238:239], v[88:89], s[98:99] op_sel_hi:[1,0]
	v_pk_mul_f32 v[240:241], v[90:91], s[98:99] op_sel_hi:[1,0]
	v_exp_f32_e32 v234, v234
	v_exp_f32_e32 v235, v235
	v_exp_f32_e32 v236, v236
	v_exp_f32_e32 v237, v237
	v_exp_f32_e32 v238, v238
	v_exp_f32_e32 v239, v239
	v_exp_f32_e32 v240, v240
	v_exp_f32_e32 v241, v241
	v_pk_add_f32 v[234:235], v[234:235], s[100:101] op_sel_hi:[1,0]
	v_pk_add_f32 v[236:237], v[236:237], s[100:101] op_sel_hi:[1,0]
	v_pk_add_f32 v[238:239], v[238:239], s[100:101] op_sel_hi:[1,0]
	v_pk_add_f32 v[240:241], v[240:241], s[100:101] op_sel_hi:[1,0]
	v_rcp_f32_e32 v234, v234
	v_rcp_f32_e32 v235, v235
	v_rcp_f32_e32 v236, v236
	v_rcp_f32_e32 v237, v237
	v_rcp_f32_e32 v238, v238
	v_rcp_f32_e32 v239, v239
	v_rcp_f32_e32 v240, v240
	v_rcp_f32_e32 v241, v241
	v_pk_mul_f32 v[234:235], v[92:93], v[234:235]
	v_pk_mul_f32 v[236:237], v[94:95], v[236:237]
	v_pk_mul_f32 v[238:239], v[88:89], v[238:239]
	v_pk_mul_f32 v[240:241], v[90:91], v[240:241]
	v_pk_mul_f32 v[234:235], v[234:235], v[84:85]
	v_pk_mul_f32 v[236:237], v[236:237], v[86:87]
	v_pk_mul_f32 v[238:239], v[238:239], v[80:81]
	v_pk_mul_f32 v[240:241], v[240:241], v[82:83]
	v_cvt_pk_bf16_f32 v84, v234, v235
	v_cvt_pk_bf16_f32 v85, v236, v237
	v_cvt_pk_bf16_f32 v86, v238, v239
	v_cvt_pk_bf16_f32 v87, v240, v241
	global_store_dwordx4 v[96:97], v[84:87], off
	v_or_b32_e32 v80, 48, v154
	v_mad_i64_i32 v[80:81], s[0:1], v80, s58, v[144:145]
	v_lshl_add_u64 v[80:81], v[80:81], 0, v[146:147]
	v_pk_mul_f32 v[234:235], v[76:77], s[98:99] op_sel_hi:[1,0]
	v_pk_mul_f32 v[236:237], v[78:79], s[98:99] op_sel_hi:[1,0]
	v_pk_mul_f32 v[238:239], v[72:73], s[98:99] op_sel_hi:[1,0]
	v_pk_mul_f32 v[240:241], v[74:75], s[98:99] op_sel_hi:[1,0]
	v_exp_f32_e32 v234, v234
	v_exp_f32_e32 v235, v235
	v_exp_f32_e32 v236, v236
	v_exp_f32_e32 v237, v237
	v_exp_f32_e32 v238, v238
; __device__ __forceinline__ unsigned cvt_pk_bf16(float lo, float hi) { unsigned r; asm volatile("v_cvt_pk_bf16_f32 %0, %1, %2" : "=v"(r) : "v"(lo), "v"(hi)); return r; }
; __device__ __forceinline__ float silu_f(float x) { return x * sigmoid_f(x); }
;     __device__ __forceinline__ void operator()(const f32x4 (&acc)[2][2][4][2], const Unit& u, int wr, int wc, int fr, int fq) const {
;         const int row0 = u.pm * BM + wr * 64 + fr; const int col0 = u.pn * HALF + wc * 32 + 8 * fq;
; #pragma unroll
;         for (int ai = 0; ai < 2; ++ai)
; #pragma unroll
;             for (int m = 0; m < 4; ++m) {
;                 bf16_t* rowp = O + (size_t)(row0 + ai * HALF + m * 16) * ldc + col0;
;                 const f32x4 g0 = acc[ai][0][m][0], g1 = acc[ai][0][m][1], u0 = acc[ai][1][m][0], u1 = acc[ai][1][m][1];
;                 u32x4 w;
;                 w.x = cvt_pk_bf16(silu_f(g0[0]) * u0[0], silu_f(g0[1]) * u0[1]); w.y = cvt_pk_bf16(silu_f(g0[2]) * u0[2], silu_f(g0[3]) * u0[3]);
;                 w.z = cvt_pk_bf16(silu_f(g1[0]) * u1[0], silu_f(g1[1]) * u1[1]); w.w = cvt_pk_bf16(silu_f(g1[2]) * u1[2], silu_f(g1[3]) * u1[3]);
;                 *(u32x4*)rowp = w;
;             }
	v_exp_f32_e32 v239, v239
	v_exp_f32_e32 v240, v240
	v_exp_f32_e32 v241, v241
	v_pk_add_f32 v[234:235], v[234:235], s[100:101] op_sel_hi:[1,0]
	v_pk_add_f32 v[236:237], v[236:237], s[100:101] op_sel_hi:[1,0]
	v_pk_add_f32 v[238:239], v[238:239], s[100:101] op_sel_hi:[1,0]
	v_pk_add_f32 v[240:241], v[240:241], s[100:101] op_sel_hi:[1,0]
	v_rcp_f32_e32 v234, v234
	v_rcp_f32_e32 v235, v235
	v_rcp_f32_e32 v236, v236
	v_rcp_f32_e32 v237, v237
	v_rcp_f32_e32 v238, v238
	v_rcp_f32_e32 v239, v239
	v_rcp_f32_e32 v240, v240
	v_rcp_f32_e32 v241, v241
	v_pk_mul_f32 v[234:235], v[76:77], v[234:235]
	v_pk_mul_f32 v[236:237], v[78:79], v[236:237]
	v_pk_mul_f32 v[238:239], v[72:73], v[238:239]
	v_pk_mul_f32 v[240:241], v[74:75], v[240:241]
	v_pk_mul_f32 v[234:235], v[234:235], v[68:69]
	v_pk_mul_f32 v[236:237], v[236:237], v[70:71]
	v_pk_mul_f32 v[238:239], v[238:239], v[64:65]
	v_pk_mul_f32 v[240:241], v[240:241], v[66:67]
	v_cvt_pk_bf16_f32 v68, v234, v235
	v_cvt_pk_bf16_f32 v69, v236, v237
	v_cvt_pk_bf16_f32 v70, v238, v239
	v_cvt_pk_bf16_f32 v71, v240, v241
	global_store_dwordx4 v[80:81], v[68:71], off
	v_add_u32_e32 v64, 0x80, v154
	v_mad_i64_i32 v[64:65], s[0:1], v64, s58, v[144:145]
	v_lshl_add_u64 v[64:65], v[64:65], 0, v[146:147]
	v_pk_mul_f32 v[234:235], v[60:61], s[98:99] op_sel_hi:[1,0]
	v_pk_mul_f32 v[236:237], v[62:63], s[98:99] op_sel_hi:[1,0]
	v_pk_mul_f32 v[238:239], v[56:57], s[98:99] op_sel_hi:[1,0]
	v_pk_mul_f32 v[240:241], v[58:59], s[98:99] op_sel_hi:[1,0]
	v_exp_f32_e32 v234, v234
	v_exp_f32_e32 v235, v235
	v_exp_f32_e32 v236, v236
	v_exp_f32_e32 v237, v237
	v_exp_f32_e32 v238, v238
	v_exp_f32_e32 v239, v239
	v_exp_f32_e32 v240, v240
	v_exp_f32_e32 v241, v241
	v_pk_add_f32 v[234:235], v[234:235], s[100:101] op_sel_hi:[1,0]
	v_pk_add_f32 v[236:237], v[236:237], s[100:101] op_sel_hi:[1,0]
	v_pk_add_f32 v[238:239], v[238:239], s[100:101] op_sel_hi:[1,0]
	v_pk_add_f32 v[240:241], v[240:241], s[100:101] op_sel_hi:[1,0]
	v_rcp_f32_e32 v234, v234
	v_rcp_f32_e32 v235, v235
	v_rcp_f32_e32 v236, v236
	v_rcp_f32_e32 v237, v237
	v_rcp_f32_e32 v238, v238
	v_rcp_f32_e32 v239, v239
	v_rcp_f32_e32 v240, v240
	v_rcp_f32_e32 v241, v241
	v_pk_mul_f32 v[234:235], v[60:61], v[234:235]
	v_pk_mul_f32 v[236:237], v[62:63], v[236:237]
	v_pk_mul_f32 v[238:239], v[56:57], v[238:239]
	v_pk_mul_f32 v[240:241], v[58:59], v[240:241]
	v_pk_mul_f32 v[234:235], v[234:235], v[52:53]
	v_pk_mul_f32 v[236:237], v[236:237], v[54:55]
	v_pk_mul_f32 v[238:239], v[238:239], v[48:49]
	v_pk_mul_f32 v[240:241], v[240:241], v[50:51]
	v_cvt_pk_bf16_f32 v52, v234, v235
	v_cvt_pk_bf16_f32 v53, v236, v237
	v_cvt_pk_bf16_f32 v54, v238, v239
	v_cvt_pk_bf16_f32 v55, v240, v241
	global_store_dwordx4 v[64:65], v[52:55], off
	v_add_u32_e32 v48, 0x90, v154
	v_mad_i64_i32 v[48:49], s[0:1], v48, s58, v[144:145]
	v_lshl_add_u64 v[48:49], v[48:49], 0, v[146:147]
	v_pk_mul_f32 v[234:235], v[44:45], s[98:99] op_sel_hi:[1,0]
	v_pk_mul_f32 v[236:237], v[46:47], s[98:99] op_sel_hi:[1,0]
	v_pk_mul_f32 v[238:239], v[40:41], s[98:99] op_sel_hi:[1,0]
	v_pk_mul_f32 v[240:241], v[42:43], s[98:99] op_sel_hi:[1,0]
	v_exp_f32_e32 v234, v234
	v_exp_f32_e32 v235, v235
	v_exp_f32_e32 v236, v236
	v_exp_f32_e32 v237, v237
	v_exp_f32_e32 v238, v238
	v_exp_f32_e32 v239, v239
	v_exp_f32_e32 v240, v240
	v_exp_f32_e32 v241, v241
	v_pk_add_f32 v[234:235], v[234:235], s[100:101] op_sel_hi:[1,0]
	v_pk_add_f32 v[236:237], v[236:237], s[100:101] op_sel_hi:[1,0]
	v_pk_add_f32 v[238:239], v[238:239], s[100:101] op_sel_hi:[1,0]
	v_pk_add_f32 v[240:241], v[240:241], s[100:101] op_sel_hi:[1,0]
	v_rcp_f32_e32 v234, v234
	v_rcp_f32_e32 v235, v235
	v_rcp_f32_e32 v236, v236
	v_rcp_f32_e32 v237, v237
	v_rcp_f32_e32 v238, v238
	v_rcp_f32_e32 v239, v239
	v_rcp_f32_e32 v240, v240
	v_rcp_f32_e32 v241, v241
	v_pk_mul_f32 v[234:235], v[44:45], v[234:235]
	v_pk_mul_f32 v[236:237], v[46:47], v[236:237]
; __device__ __forceinline__ unsigned cvt_pk_bf16(float lo, float hi) { unsigned r; asm volatile("v_cvt_pk_bf16_f32 %0, %1, %2" : "=v"(r) : "v"(lo), "v"(hi)); return r; }
; __device__ __forceinline__ float silu_f(float x) { return x * sigmoid_f(x); }
; #define PG8_BAR __builtin_amdgcn_s_barrier()
;     __device__ __forceinline__ void operator()(const f32x4 (&acc)[2][2][4][2], const Unit& u, int wr, int wc, int fr, int fq) const {
;         const int row0 = u.pm * BM + wr * 64 + fr; const int col0 = u.pn * HALF + wc * 32 + 8 * fq;
; #pragma unroll
;         for (int ai = 0; ai < 2; ++ai)
; #pragma unroll
;             for (int m = 0; m < 4; ++m) {
;                 bf16_t* rowp = O + (size_t)(row0 + ai * HALF + m * 16) * ldc + col0;
;                 const f32x4 g0 = acc[ai][0][m][0], g1 = acc[ai][0][m][1], u0 = acc[ai][1][m][0], u1 = acc[ai][1][m][1];
;                 u32x4 w;
;                 w.x = cvt_pk_bf16(silu_f(g0[0]) * u0[0], silu_f(g0[1]) * u0[1]); w.y = cvt_pk_bf16(silu_f(g0[2]) * u0[2], silu_f(g0[3]) * u0[3]);
;                 w.z = cvt_pk_bf16(silu_f(g1[0]) * u1[0], silu_f(g1[1]) * u1[1]); w.w = cvt_pk_bf16(silu_f(g1[2]) * u1[2], silu_f(g1[3]) * u1[3]);
;                 *(u32x4*)rowp = w;
;             }
; template <class Epi, class Sched, bool ALIGN_EPI = false, bool SP2 = false>
; __device__ __forceinline__ void gemm_phase(PG8_LAS unsigned char* lds, const Gemm g, const Sched& S, const Epi& E) {
;     ...
;         if (!has_next) break;
; #pragma unroll
;         for (int a = 0; a < 2; ++a)
; #pragma unroll
;             for (int b = 0; b < 2; ++b)
; #pragma unroll
;                 for (int m = 0; m < 4; ++m)
; #pragma unroll
;                     for (int n = 0; n < 2; ++n) acc[a][b][m][n] = (f32x4){0.f, 0.f, 0.f, 0.f};
;         cur = nxt; cA = nA; cB = nB; ++ui;
;         if constexpr (ALIGN_EPI) { if (wr == 1) PG8_BAR; }
	v_pk_mul_f32 v[238:239], v[40:41], v[238:239]
	v_pk_mul_f32 v[240:241], v[42:43], v[240:241]
	v_pk_mul_f32 v[234:235], v[234:235], v[36:37]
	v_pk_mul_f32 v[236:237], v[236:237], v[38:39]
	v_pk_mul_f32 v[238:239], v[238:239], v[32:33]
	v_pk_mul_f32 v[240:241], v[240:241], v[34:35]
	v_cvt_pk_bf16_f32 v36, v234, v235
	v_cvt_pk_bf16_f32 v37, v236, v237
	v_cvt_pk_bf16_f32 v38, v238, v239
	v_cvt_pk_bf16_f32 v39, v240, v241
	global_store_dwordx4 v[48:49], v[36:39], off
	v_add_u32_e32 v32, 0xa0, v154
	v_mad_i64_i32 v[32:33], s[0:1], v32, s58, v[144:145]
	v_lshl_add_u64 v[32:33], v[32:33], 0, v[146:147]
	v_pk_mul_f32 v[234:235], v[28:29], s[98:99] op_sel_hi:[1,0]
	v_pk_mul_f32 v[236:237], v[30:31], s[98:99] op_sel_hi:[1,0]
	v_pk_mul_f32 v[238:239], v[24:25], s[98:99] op_sel_hi:[1,0]
	v_pk_mul_f32 v[240:241], v[26:27], s[98:99] op_sel_hi:[1,0]
	v_exp_f32_e32 v234, v234
	v_exp_f32_e32 v235, v235
	v_exp_f32_e32 v236, v236
	v_exp_f32_e32 v237, v237
	v_exp_f32_e32 v238, v238
	v_exp_f32_e32 v239, v239
	v_exp_f32_e32 v240, v240
	v_exp_f32_e32 v241, v241
	v_pk_add_f32 v[234:235], v[234:235], s[100:101] op_sel_hi:[1,0]
	v_pk_add_f32 v[236:237], v[236:237], s[100:101] op_sel_hi:[1,0]
	v_pk_add_f32 v[238:239], v[238:239], s[100:101] op_sel_hi:[1,0]
	v_pk_add_f32 v[240:241], v[240:241], s[100:101] op_sel_hi:[1,0]
	v_rcp_f32_e32 v234, v234
	v_rcp_f32_e32 v235, v235
	v_rcp_f32_e32 v236, v236
	v_rcp_f32_e32 v237, v237
	v_rcp_f32_e32 v238, v238
	v_rcp_f32_e32 v239, v239
	v_rcp_f32_e32 v240, v240
	v_rcp_f32_e32 v241, v241
	v_pk_mul_f32 v[234:235], v[28:29], v[234:235]
	v_pk_mul_f32 v[236:237], v[30:31], v[236:237]
	v_pk_mul_f32 v[238:239], v[24:25], v[238:239]
	v_pk_mul_f32 v[240:241], v[26:27], v[240:241]
	v_pk_mul_f32 v[234:235], v[234:235], v[20:21]
	v_pk_mul_f32 v[236:237], v[236:237], v[22:23]
	v_pk_mul_f32 v[238:239], v[238:239], v[16:17]
	v_pk_mul_f32 v[240:241], v[240:241], v[18:19]
	v_cvt_pk_bf16_f32 v20, v234, v235
	v_cvt_pk_bf16_f32 v21, v236, v237
	v_cvt_pk_bf16_f32 v22, v238, v239
	v_cvt_pk_bf16_f32 v23, v240, v241
	global_store_dwordx4 v[32:33], v[20:23], off
	v_add_u32_e32 v16, 0xb0, v154
	v_mad_i64_i32 v[16:17], s[0:1], v16, s58, v[144:145]
	v_lshl_add_u64 v[16:17], v[16:17], 0, v[146:147]
	s_andn2_b64 vcc, exec, s[4:5]
	s_mov_b64 s[4:5], -1
	v_pk_mul_f32 v[234:235], v[12:13], s[98:99] op_sel_hi:[1,0]
	v_pk_mul_f32 v[236:237], v[14:15], s[98:99] op_sel_hi:[1,0]
	v_pk_mul_f32 v[238:239], v[8:9], s[98:99] op_sel_hi:[1,0]
	v_pk_mul_f32 v[240:241], v[10:11], s[98:99] op_sel_hi:[1,0]
	v_exp_f32_e32 v234, v234
	v_exp_f32_e32 v235, v235
	v_exp_f32_e32 v236, v236
	v_exp_f32_e32 v237, v237
	v_exp_f32_e32 v238, v238
	v_exp_f32_e32 v239, v239
	v_exp_f32_e32 v240, v240
	v_exp_f32_e32 v241, v241
	v_pk_add_f32 v[234:235], v[234:235], s[100:101] op_sel_hi:[1,0]
	v_pk_add_f32 v[236:237], v[236:237], s[100:101] op_sel_hi:[1,0]
	v_pk_add_f32 v[238:239], v[238:239], s[100:101] op_sel_hi:[1,0]
	v_pk_add_f32 v[240:241], v[240:241], s[100:101] op_sel_hi:[1,0]
	v_rcp_f32_e32 v234, v234
	v_rcp_f32_e32 v235, v235
	v_rcp_f32_e32 v236, v236
	v_rcp_f32_e32 v237, v237
	v_rcp_f32_e32 v238, v238
	v_rcp_f32_e32 v239, v239
	v_rcp_f32_e32 v240, v240
	v_rcp_f32_e32 v241, v241
	v_pk_mul_f32 v[234:235], v[12:13], v[234:235]
	v_pk_mul_f32 v[236:237], v[14:15], v[236:237]
	v_pk_mul_f32 v[238:239], v[8:9], v[238:239]
	v_pk_mul_f32 v[240:241], v[10:11], v[240:241]
	v_pk_mul_f32 v[234:235], v[234:235], v[4:5]
	v_pk_mul_f32 v[236:237], v[236:237], v[6:7]
	v_pk_mul_f32 v[238:239], v[238:239], v[0:1]
	v_pk_mul_f32 v[240:241], v[240:241], v[2:3]
	v_cvt_pk_bf16_f32 v4, v234, v235
	v_cvt_pk_bf16_f32 v5, v236, v237
	v_cvt_pk_bf16_f32 v6, v238, v239
	v_cvt_pk_bf16_f32 v7, v240, v241
	global_store_dwordx4 v[16:17], v[4:7], off
	s_cbranch_vccnz .LBB0_208
	s_andn2_b64 vcc, exec, s[8:9]
	s_cbranch_vccnz .LBB0_207
	s_barrier
	s_branch .LBB0_207

; __device__ __forceinline__ unsigned cvt_pk_bf16(float lo, float hi) { unsigned r; asm volatile("v_cvt_pk_bf16_f32 %0, %1, %2" : "=v"(r) : "v"(lo), "v"(hi)); return r; }
; __device__ __forceinline__ float sigmoid_f(float x) { return __builtin_amdgcn_rcpf(1.0f + __expf(-x)); }
; __device__ __forceinline__ float silu_f(float x) { return x * sigmoid_f(x); }
;     __device__ __forceinline__ void operator()(const f32x4 (&acc)[2][2][4][2], const Unit& u, int wr, int wc, int fr, int fq) const {
;     ...
;                 bf16_t* rowp = O + (size_t)(row0 + ai * HALF + m * 16) * ldc + col0;
;                 const f32x4 g0 = acc[ai][0][m][0], g1 = acc[ai][0][m][1], u0 = acc[ai][1][m][0], u1 = acc[ai][1][m][1];
;                 u32x4 w;
;                 w.x = cvt_pk_bf16(silu_f(g0[0]) * u0[0], silu_f(g0[1]) * u0[1]); w.y = cvt_pk_bf16(silu_f(g0[2]) * u0[2], silu_f(g0[3]) * u0[3]);
;                 w.z = cvt_pk_bf16(silu_f(g1[0]) * u1[0], silu_f(g1[1]) * u1[1]); w.w = cvt_pk_bf16(silu_f(g1[2]) * u1[2], silu_f(g1[3]) * u1[3]);
;                 *(u32x4*)rowp = w;
.LBB0_1121:
	v_lshl_or_b32 v146, s59, 7, v150
	v_lshl_add_u32 v154, s28, 8, v148
	v_ashrrev_i32_e32 v147, 31, v146
	v_mov_b64_e32 v[144:145], s[14:15]
	v_mad_i64_i32 v[156:157], s[0:1], v154, s58, v[144:145]
	v_lshlrev_b64 v[146:147], 1, v[146:147]
	v_lshl_add_u64 v[156:157], v[156:157], 0, v[146:147]
	s_mov_b32 s98, 0xbfb8aa3b
	s_mov_b32 s100, 1.0
	v_pk_mul_f32 v[234:235], v[124:125], s[98:99] op_sel_hi:[1,0]
	v_pk_mul_f32 v[236:237], v[126:127], s[98:99] op_sel_hi:[1,0]
	v_pk_mul_f32 v[238:239], v[120:121], s[98:99] op_sel_hi:[1,0]
	v_pk_mul_f32 v[240:241], v[122:123], s[98:99] op_sel_hi:[1,0]
	v_exp_f32_e32 v234, v234
	v_exp_f32_e32 v235, v235
	v_exp_f32_e32 v236, v236
	v_exp_f32_e32 v237, v237
	v_exp_f32_e32 v238, v238
	v_exp_f32_e32 v239, v239
	v_exp_f32_e32 v240, v240
	v_exp_f32_e32 v241, v241
	v_pk_add_f32 v[234:235], v[234:235], s[100:101] op_sel_hi:[1,0]
	v_pk_add_f32 v[236:237], v[236:237], s[100:101] op_sel_hi:[1,0]
	v_pk_add_f32 v[238:239], v[238:239], s[100:101] op_sel_hi:[1,0]
	v_pk_add_f32 v[240:241], v[240:241], s[100:101] op_sel_hi:[1,0]
	v_rcp_f32_e32 v234, v234
	v_rcp_f32_e32 v235, v235
	v_rcp_f32_e32 v236, v236
	v_rcp_f32_e32 v237, v237
	v_rcp_f32_e32 v238, v238
	v_rcp_f32_e32 v239, v239
	v_rcp_f32_e32 v240, v240
	v_rcp_f32_e32 v241, v241
	v_pk_mul_f32 v[234:235], v[124:125], v[234:235]
	v_pk_mul_f32 v[236:237], v[126:127], v[236:237]
	v_pk_mul_f32 v[238:239], v[120:121], v[238:239]
	v_pk_mul_f32 v[240:241], v[122:123], v[240:241]
	v_pk_mul_f32 v[234:235], v[234:235], v[116:117]
	v_pk_mul_f32 v[236:237], v[236:237], v[118:119]
	v_pk_mul_f32 v[238:239], v[238:239], v[112:113]
	v_pk_mul_f32 v[240:241], v[240:241], v[114:115]
	v_cvt_pk_bf16_f32 v116, v234, v235
	v_cvt_pk_bf16_f32 v117, v236, v237
	v_cvt_pk_bf16_f32 v118, v238, v239
	v_cvt_pk_bf16_f32 v119, v240, v241
	global_store_dwordx4 v[156:157], v[116:119], off
	v_or_b32_e32 v112, 16, v154
	v_mad_i64_i32 v[112:113], s[0:1], v112, s58, v[144:145]
	v_lshl_add_u64 v[112:113], v[112:113], 0, v[146:147]
	v_pk_mul_f32 v[234:235], v[108:109], s[98:99] op_sel_hi:[1,0]
	v_pk_mul_f32 v[236:237], v[110:111], s[98:99] op_sel_hi:[1,0]
	v_pk_mul_f32 v[238:239], v[104:105], s[98:99] op_sel_hi:[1,0]
	v_pk_mul_f32 v[240:241], v[106:107], s[98:99] op_sel_hi:[1,0]
	v_exp_f32_e32 v234, v234
	v_exp_f32_e32 v235, v235
	v_exp_f32_e32 v236, v236
	v_exp_f32_e32 v237, v237
	v_exp_f32_e32 v238, v238
	v_exp_f32_e32 v239, v239
	v_exp_f32_e32 v240, v240
	v_exp_f32_e32 v241, v241
	v_pk_add_f32 v[234:235], v[234:235], s[100:101] op_sel_hi:[1,0]
	v_pk_add_f32 v[236:237], v[236:237], s[100:101] op_sel_hi:[1,0]
	v_pk_add_f32 v[238:239], v[238:239], s[100:101] op_sel_hi:[1,0]
	v_pk_add_f32 v[240:241], v[240:241], s[100:101] op_sel_hi:[1,0]
	v_rcp_f32_e32 v234, v234
	v_rcp_f32_e32 v235, v235
	v_rcp_f32_e32 v236, v236
	v_rcp_f32_e32 v237, v237
	v_rcp_f32_e32 v238, v238
	v_rcp_f32_e32 v239, v239
	v_rcp_f32_e32 v240, v240
	v_rcp_f32_e32 v241, v241
	v_pk_mul_f32 v[234:235], v[108:109], v[234:235]
	v_pk_mul_f32 v[236:237], v[110:111], v[236:237]
	v_pk_mul_f32 v[238:239], v[104:105], v[238:239]
	v_pk_mul_f32 v[240:241], v[106:107], v[240:241]
	v_pk_mul_f32 v[234:235], v[234:235], v[100:101]
	v_pk_mul_f32 v[236:237], v[236:237], v[102:103]
	v_pk_mul_f32 v[238:239], v[238:239], v[96:97]
	v_pk_mul_f32 v[240:241], v[240:241], v[98:99]
	v_cvt_pk_bf16_f32 v100, v234, v235
	v_cvt_pk_bf16_f32 v101, v236, v237
	v_cvt_pk_bf16_f32 v102, v238, v239
	v_cvt_pk_bf16_f32 v103, v240, v241
	global_store_dwordx4 v[112:113], v[100:103], off
	v_or_b32_e32 v96, 32, v154
	v_mad_i64_i32 v[96:97], s[0:1], v96, s58, v[144:145]
	v_lshl_add_u64 v[96:97], v[96:97], 0, v[146:147]
	v_pk_mul_f32 v[234:235], v[92:93], s[98:99] op_sel_hi:[1,0]
	v_pk_mul_f32 v[236:237], v[94:95], s[98:99] op_sel_hi:[1,0]
	v_pk_mul_f32 v[238:239], v[88:89], s[98:99] op_sel_hi:[1,0]
	v_pk_mul_f32 v[240:241], v[90:91], s[98:99] op_sel_hi:[1,0]
	v_exp_f32_e32 v234, v234
	v_exp_f32_e32 v235, v235
	v_exp_f32_e32 v236, v236
	v_exp_f32_e32 v237, v237
	v_exp_f32_e32 v238, v238
	v_exp_f32_e32 v239, v239
	v_exp_f32_e32 v240, v240
	v_exp_f32_e32 v241, v241
	v_pk_add_f32 v[234:235], v[234:235], s[100:101] op_sel_hi:[1,0]
	v_pk_add_f32 v[236:237], v[236:237], s[100:101] op_sel_hi:[1,0]
	v_pk_add_f32 v[238:239], v[238:239], s[100:101] op_sel_hi:[1,0]
	v_pk_add_f32 v[240:241], v[240:241], s[100:101] op_sel_hi:[1,0]
	v_rcp_f32_e32 v234, v234
	v_rcp_f32_e32 v235, v235
	v_rcp_f32_e32 v236, v236
	v_rcp_f32_e32 v237, v237
	v_rcp_f32_e32 v238, v238
	v_rcp_f32_e32 v239, v239
	v_rcp_f32_e32 v240, v240
	v_rcp_f32_e32 v241, v241
	v_pk_mul_f32 v[234:235], v[92:93], v[234:235]
	v_pk_mul_f32 v[236:237], v[94:95], v[236:237]
	v_pk_mul_f32 v[238:239], v[88:89], v[238:239]
	v_pk_mul_f32 v[240:241], v[90:91], v[240:241]
	v_pk_mul_f32 v[234:235], v[234:235], v[84:85]
	v_pk_mul_f32 v[236:237], v[236:237], v[86:87]
	v_pk_mul_f32 v[238:239], v[238:239], v[80:81]
	v_pk_mul_f32 v[240:241], v[240:241], v[82:83]
	v_cvt_pk_bf16_f32 v84, v234, v235
	v_cvt_pk_bf16_f32 v85, v236, v237
	v_cvt_pk_bf16_f32 v86, v238, v239
	v_cvt_pk_bf16_f32 v87, v240, v241
	global_store_dwordx4 v[96:97], v[84:87], off
	v_or_b32_e32 v80, 48, v154
	v_mad_i64_i32 v[80:81], s[0:1], v80, s58, v[144:145]
	v_lshl_add_u64 v[80:81], v[80:81], 0, v[146:147]
	v_pk_mul_f32 v[234:235], v[76:77], s[98:99] op_sel_hi:[1,0]
	v_pk_mul_f32 v[236:237], v[78:79], s[98:99] op_sel_hi:[1,0]
	v_pk_mul_f32 v[238:239], v[72:73], s[98:99] op_sel_hi:[1,0]
	v_pk_mul_f32 v[240:241], v[74:75], s[98:99] op_sel_hi:[1,0]
	v_exp_f32_e32 v234, v234
	v_exp_f32_e32 v235, v235
	v_exp_f32_e32 v236, v236
	v_exp_f32_e32 v237, v237
	v_exp_f32_e32 v238, v238
; __device__ __forceinline__ unsigned cvt_pk_bf16(float lo, float hi) { unsigned r; asm volatile("v_cvt_pk_bf16_f32 %0, %1, %2" : "=v"(r) : "v"(lo), "v"(hi)); return r; }
; __device__ __forceinline__ float silu_f(float x) { return x * sigmoid_f(x); }
;     __device__ __forceinline__ void operator()(const f32x4 (&acc)[2][2][4][2], const Unit& u, int wr, int wc, int fr, int fq) const {
;     ...
;                 bf16_t* rowp = O + (size_t)(row0 + ai * HALF + m * 16) * ldc + col0;
;                 const f32x4 g0 = acc[ai][0][m][0], g1 = acc[ai][0][m][1], u0 = acc[ai][1][m][0], u1 = acc[ai][1][m][1];
;                 u32x4 w;
;                 w.x = cvt_pk_bf16(silu_f(g0[0]) * u0[0], silu_f(g0[1]) * u0[1]); w.y = cvt_pk_bf16(silu_f(g0[2]) * u0[2], silu_f(g0[3]) * u0[3]);
;                 w.z = cvt_pk_bf16(silu_f(g1[0]) * u1[0], silu_f(g1[1]) * u1[1]); w.w = cvt_pk_bf16(silu_f(g1[2]) * u1[2], silu_f(g1[3]) * u1[3]);
;                 *(u32x4*)rowp = w;
	v_exp_f32_e32 v239, v239
	v_exp_f32_e32 v240, v240
	v_exp_f32_e32 v241, v241
	v_pk_add_f32 v[234:235], v[234:235], s[100:101] op_sel_hi:[1,0]
	v_pk_add_f32 v[236:237], v[236:237], s[100:101] op_sel_hi:[1,0]
	v_pk_add_f32 v[238:239], v[238:239], s[100:101] op_sel_hi:[1,0]
	v_pk_add_f32 v[240:241], v[240:241], s[100:101] op_sel_hi:[1,0]
	v_rcp_f32_e32 v234, v234
	v_rcp_f32_e32 v235, v235
	v_rcp_f32_e32 v236, v236
	v_rcp_f32_e32 v237, v237
	v_rcp_f32_e32 v238, v238
	v_rcp_f32_e32 v239, v239
	v_rcp_f32_e32 v240, v240
	v_rcp_f32_e32 v241, v241
	v_pk_mul_f32 v[234:235], v[76:77], v[234:235]
	v_pk_mul_f32 v[236:237], v[78:79], v[236:237]
	v_pk_mul_f32 v[238:239], v[72:73], v[238:239]
	v_pk_mul_f32 v[240:241], v[74:75], v[240:241]
	v_pk_mul_f32 v[234:235], v[234:235], v[68:69]
	v_pk_mul_f32 v[236:237], v[236:237], v[70:71]
	v_pk_mul_f32 v[238:239], v[238:239], v[64:65]
	v_pk_mul_f32 v[240:241], v[240:241], v[66:67]
	v_cvt_pk_bf16_f32 v68, v234, v235
	v_cvt_pk_bf16_f32 v69, v236, v237
	v_cvt_pk_bf16_f32 v70, v238, v239
	v_cvt_pk_bf16_f32 v71, v240, v241
	global_store_dwordx4 v[80:81], v[68:71], off
	v_add_u32_e32 v64, 0x80, v154
	v_mad_i64_i32 v[64:65], s[0:1], v64, s58, v[144:145]
	v_lshl_add_u64 v[64:65], v[64:65], 0, v[146:147]
	v_pk_mul_f32 v[234:235], v[60:61], s[98:99] op_sel_hi:[1,0]
	v_pk_mul_f32 v[236:237], v[62:63], s[98:99] op_sel_hi:[1,0]
	v_pk_mul_f32 v[238:239], v[56:57], s[98:99] op_sel_hi:[1,0]
	v_pk_mul_f32 v[240:241], v[58:59], s[98:99] op_sel_hi:[1,0]
	v_exp_f32_e32 v234, v234
	v_exp_f32_e32 v235, v235
	v_exp_f32_e32 v236, v236
	v_exp_f32_e32 v237, v237
	v_exp_f32_e32 v238, v238
	v_exp_f32_e32 v239, v239
	v_exp_f32_e32 v240, v240
	v_exp_f32_e32 v241, v241
	v_pk_add_f32 v[234:235], v[234:235], s[100:101] op_sel_hi:[1,0]
	v_pk_add_f32 v[236:237], v[236:237], s[100:101] op_sel_hi:[1,0]
	v_pk_add_f32 v[238:239], v[238:239], s[100:101] op_sel_hi:[1,0]
	v_pk_add_f32 v[240:241], v[240:241], s[100:101] op_sel_hi:[1,0]
	v_rcp_f32_e32 v234, v234
	v_rcp_f32_e32 v235, v235
	v_rcp_f32_e32 v236, v236
	v_rcp_f32_e32 v237, v237
	v_rcp_f32_e32 v238, v238
	v_rcp_f32_e32 v239, v239
	v_rcp_f32_e32 v240, v240
	v_rcp_f32_e32 v241, v241
	v_pk_mul_f32 v[234:235], v[60:61], v[234:235]
	v_pk_mul_f32 v[236:237], v[62:63], v[236:237]
	v_pk_mul_f32 v[238:239], v[56:57], v[238:239]
	v_pk_mul_f32 v[240:241], v[58:59], v[240:241]
	v_pk_mul_f32 v[234:235], v[234:235], v[52:53]
	v_pk_mul_f32 v[236:237], v[236:237], v[54:55]
	v_pk_mul_f32 v[238:239], v[238:239], v[48:49]
	v_pk_mul_f32 v[240:241], v[240:241], v[50:51]
	v_cvt_pk_bf16_f32 v52, v234, v235
	v_cvt_pk_bf16_f32 v53, v236, v237
	v_cvt_pk_bf16_f32 v54, v238, v239
	v_cvt_pk_bf16_f32 v55, v240, v241
	global_store_dwordx4 v[64:65], v[52:55], off
	v_add_u32_e32 v48, 0x90, v154
	v_mad_i64_i32 v[48:49], s[0:1], v48, s58, v[144:145]
	v_lshl_add_u64 v[48:49], v[48:49], 0, v[146:147]
	v_pk_mul_f32 v[234:235], v[44:45], s[98:99] op_sel_hi:[1,0]
	v_pk_mul_f32 v[236:237], v[46:47], s[98:99] op_sel_hi:[1,0]
	v_pk_mul_f32 v[238:239], v[40:41], s[98:99] op_sel_hi:[1,0]
	v_pk_mul_f32 v[240:241], v[42:43], s[98:99] op_sel_hi:[1,0]
	v_exp_f32_e32 v234, v234
	v_exp_f32_e32 v235, v235
	v_exp_f32_e32 v236, v236
	v_exp_f32_e32 v237, v237
	v_exp_f32_e32 v238, v238
	v_exp_f32_e32 v239, v239
	v_exp_f32_e32 v240, v240
	v_exp_f32_e32 v241, v241
	v_pk_add_f32 v[234:235], v[234:235], s[100:101] op_sel_hi:[1,0]
	v_pk_add_f32 v[236:237], v[236:237], s[100:101] op_sel_hi:[1,0]
	v_pk_add_f32 v[238:239], v[238:239], s[100:101] op_sel_hi:[1,0]
	v_pk_add_f32 v[240:241], v[240:241], s[100:101] op_sel_hi:[1,0]
	v_rcp_f32_e32 v234, v234
	v_rcp_f32_e32 v235, v235
	v_rcp_f32_e32 v236, v236
	v_rcp_f32_e32 v237, v237
	v_rcp_f32_e32 v238, v238
	v_rcp_f32_e32 v239, v239
	v_rcp_f32_e32 v240, v240
	v_rcp_f32_e32 v241, v241
	v_pk_mul_f32 v[234:235], v[44:45], v[234:235]
	v_pk_mul_f32 v[236:237], v[46:47], v[236:237]
; __device__ __forceinline__ unsigned cvt_pk_bf16(float lo, float hi) { unsigned r; asm volatile("v_cvt_pk_bf16_f32 %0, %1, %2" : "=v"(r) : "v"(lo), "v"(hi)); return r; }
; __device__ __forceinline__ float silu_f(float x) { return x * sigmoid_f(x); }
; #define PG8_BAR __builtin_amdgcn_s_barrier()
;     __device__ __forceinline__ void operator()(const f32x4 (&acc)[2][2][4][2], const Unit& u, int wr, int wc, int fr, int fq) const {
;     ...
;                 bf16_t* rowp = O + (size_t)(row0 + ai * HALF + m * 16) * ldc + col0;
;                 const f32x4 g0 = acc[ai][0][m][0], g1 = acc[ai][0][m][1], u0 = acc[ai][1][m][0], u1 = acc[ai][1][m][1];
;                 u32x4 w;
;                 w.x = cvt_pk_bf16(silu_f(g0[0]) * u0[0], silu_f(g0[1]) * u0[1]); w.y = cvt_pk_bf16(silu_f(g0[2]) * u0[2], silu_f(g0[3]) * u0[3]);
;                 w.z = cvt_pk_bf16(silu_f(g1[0]) * u1[0], silu_f(g1[1]) * u1[1]); w.w = cvt_pk_bf16(silu_f(g1[2]) * u1[2], silu_f(g1[3]) * u1[3]);
;                 *(u32x4*)rowp = w;
; template <class Epi, class Sched, bool ALIGN_EPI = false, bool SP2 = false>
; __device__ __forceinline__ void gemm_phase(PG8_LAS unsigned char* lds, const Gemm g, const Sched& S, const Epi& E) {
;     ...
;         if (!has_next) break;
; #pragma unroll
;         for (int a = 0; a < 2; ++a)
; #pragma unroll
;             for (int b = 0; b < 2; ++b)
; #pragma unroll
;                 for (int m = 0; m < 4; ++m)
; #pragma unroll
;                     for (int n = 0; n < 2; ++n) acc[a][b][m][n] = (f32x4){0.f, 0.f, 0.f, 0.f};
;         cur = nxt; cA = nA; cB = nB; ++ui;
;         if constexpr (ALIGN_EPI) { if (wr == 1) PG8_BAR; }
	v_pk_mul_f32 v[238:239], v[40:41], v[238:239]
	v_pk_mul_f32 v[240:241], v[42:43], v[240:241]
	v_pk_mul_f32 v[234:235], v[234:235], v[36:37]
	v_pk_mul_f32 v[236:237], v[236:237], v[38:39]
	v_pk_mul_f32 v[238:239], v[238:239], v[32:33]
	v_pk_mul_f32 v[240:241], v[240:241], v[34:35]
	v_cvt_pk_bf16_f32 v36, v234, v235
	v_cvt_pk_bf16_f32 v37, v236, v237
	v_cvt_pk_bf16_f32 v38, v238, v239
	v_cvt_pk_bf16_f32 v39, v240, v241
	global_store_dwordx4 v[48:49], v[36:39], off
	v_add_u32_e32 v32, 0xa0, v154
	v_mad_i64_i32 v[32:33], s[0:1], v32, s58, v[144:145]
	v_lshl_add_u64 v[32:33], v[32:33], 0, v[146:147]
	v_pk_mul_f32 v[234:235], v[28:29], s[98:99] op_sel_hi:[1,0]
	v_pk_mul_f32 v[236:237], v[30:31], s[98:99] op_sel_hi:[1,0]
	v_pk_mul_f32 v[238:239], v[24:25], s[98:99] op_sel_hi:[1,0]
	v_pk_mul_f32 v[240:241], v[26:27], s[98:99] op_sel_hi:[1,0]
	v_exp_f32_e32 v234, v234
	v_exp_f32_e32 v235, v235
	v_exp_f32_e32 v236, v236
	v_exp_f32_e32 v237, v237
	v_exp_f32_e32 v238, v238
	v_exp_f32_e32 v239, v239
	v_exp_f32_e32 v240, v240
	v_exp_f32_e32 v241, v241
	v_pk_add_f32 v[234:235], v[234:235], s[100:101] op_sel_hi:[1,0]
	v_pk_add_f32 v[236:237], v[236:237], s[100:101] op_sel_hi:[1,0]
	v_pk_add_f32 v[238:239], v[238:239], s[100:101] op_sel_hi:[1,0]
	v_pk_add_f32 v[240:241], v[240:241], s[100:101] op_sel_hi:[1,0]
	v_rcp_f32_e32 v234, v234
	v_rcp_f32_e32 v235, v235
	v_rcp_f32_e32 v236, v236
	v_rcp_f32_e32 v237, v237
	v_rcp_f32_e32 v238, v238
	v_rcp_f32_e32 v239, v239
	v_rcp_f32_e32 v240, v240
	v_rcp_f32_e32 v241, v241
	v_pk_mul_f32 v[234:235], v[28:29], v[234:235]
	v_pk_mul_f32 v[236:237], v[30:31], v[236:237]
	v_pk_mul_f32 v[238:239], v[24:25], v[238:239]
	v_pk_mul_f32 v[240:241], v[26:27], v[240:241]
	v_pk_mul_f32 v[234:235], v[234:235], v[20:21]
	v_pk_mul_f32 v[236:237], v[236:237], v[22:23]
	v_pk_mul_f32 v[238:239], v[238:239], v[16:17]
	v_pk_mul_f32 v[240:241], v[240:241], v[18:19]
	v_cvt_pk_bf16_f32 v20, v234, v235
	v_cvt_pk_bf16_f32 v21, v236, v237
	v_cvt_pk_bf16_f32 v22, v238, v239
	v_cvt_pk_bf16_f32 v23, v240, v241
	global_store_dwordx4 v[32:33], v[20:23], off
	v_add_u32_e32 v16, 0xb0, v154
	v_mad_i64_i32 v[16:17], s[0:1], v16, s58, v[144:145]
	v_lshl_add_u64 v[16:17], v[16:17], 0, v[146:147]
	s_andn2_b64 vcc, exec, s[10:11]
	s_mov_b64 s[10:11], -1
	v_pk_mul_f32 v[234:235], v[12:13], s[98:99] op_sel_hi:[1,0]
	v_pk_mul_f32 v[236:237], v[14:15], s[98:99] op_sel_hi:[1,0]
	v_pk_mul_f32 v[238:239], v[8:9], s[98:99] op_sel_hi:[1,0]
	v_pk_mul_f32 v[240:241], v[10:11], s[98:99] op_sel_hi:[1,0]
	v_exp_f32_e32 v234, v234
	v_exp_f32_e32 v235, v235
	v_exp_f32_e32 v236, v236
	v_exp_f32_e32 v237, v237
	v_exp_f32_e32 v238, v238
	v_exp_f32_e32 v239, v239
	v_exp_f32_e32 v240, v240
	v_exp_f32_e32 v241, v241
	v_pk_add_f32 v[234:235], v[234:235], s[100:101] op_sel_hi:[1,0]
	v_pk_add_f32 v[236:237], v[236:237], s[100:101] op_sel_hi:[1,0]
	v_pk_add_f32 v[238:239], v[238:239], s[100:101] op_sel_hi:[1,0]
	v_pk_add_f32 v[240:241], v[240:241], s[100:101] op_sel_hi:[1,0]
	v_rcp_f32_e32 v234, v234
	v_rcp_f32_e32 v235, v235
	v_rcp_f32_e32 v236, v236
	v_rcp_f32_e32 v237, v237
	v_rcp_f32_e32 v238, v238
	v_rcp_f32_e32 v239, v239
	v_rcp_f32_e32 v240, v240
	v_rcp_f32_e32 v241, v241
	v_pk_mul_f32 v[234:235], v[12:13], v[234:235]
	v_pk_mul_f32 v[236:237], v[14:15], v[236:237]
	v_pk_mul_f32 v[238:239], v[8:9], v[238:239]
	v_pk_mul_f32 v[240:241], v[10:11], v[240:241]
	v_pk_mul_f32 v[234:235], v[234:235], v[4:5]
	v_pk_mul_f32 v[236:237], v[236:237], v[6:7]
	v_pk_mul_f32 v[238:239], v[238:239], v[0:1]
	v_pk_mul_f32 v[240:241], v[240:241], v[2:3]
	v_cvt_pk_bf16_f32 v4, v234, v235
	v_cvt_pk_bf16_f32 v5, v236, v237
	v_cvt_pk_bf16_f32 v6, v238, v239
	v_cvt_pk_bf16_f32 v7, v240, v241
	global_store_dwordx4 v[16:17], v[4:7], off
	s_cbranch_vccnz .LBB0_1114
	s_andn2_b64 vcc, exec, s[12:13]
	s_cbranch_vccnz .LBB0_1113
	s_barrier
	s_branch .LBB0_1113

; __global__ void __launch_bounds__(NTHREADS, 2) fwd_kernel(Args args) {
	.amdhsa_kernel _Z10fwd_kernel4Args
		.amdhsa_group_segment_fixed_size 0
		.amdhsa_private_segment_fixed_size 0
		.amdhsa_kernarg_size 536
		.amdhsa_user_sgpr_count 2
		.amdhsa_user_sgpr_dispatch_ptr 0
		.amdhsa_user_sgpr_queue_ptr 0
		.amdhsa_user_sgpr_kernarg_segment_ptr 1
		.amdhsa_user_sgpr_dispatch_id 0
		.amdhsa_user_sgpr_kernarg_preload_length 0
		.amdhsa_user_sgpr_kernarg_preload_offset 0
		.amdhsa_user_sgpr_private_segment_size 0
		.amdhsa_uses_dynamic_stack 0
		.amdhsa_enable_private_segment 0
		.amdhsa_system_sgpr_workgroup_id_x 1
		.amdhsa_system_sgpr_workgroup_id_y 0
		.amdhsa_system_sgpr_workgroup_id_z 0
		.amdhsa_system_sgpr_workgroup_info 0
		.amdhsa_system_vgpr_workitem_id 2
		.amdhsa_next_free_vgpr 256
		.amdhsa_next_free_sgpr 102
		.amdhsa_accum_offset 256
		.amdhsa_reserve_vcc 1
		.amdhsa_float_round_mode_32 0
		.amdhsa_float_round_mode_16_64 0
		.amdhsa_float_denorm_mode_32 3
		.amdhsa_float_denorm_mode_16_64 3
		.amdhsa_dx10_clamp 1
		.amdhsa_ieee_mode 1
		.amdhsa_fp16_overflow 0
		.amdhsa_tg_split 0
		.amdhsa_exception_fp_ieee_invalid_op 0
		.amdhsa_exception_fp_denorm_src 0
		.amdhsa_exception_fp_ieee_div_zero 0
		.amdhsa_exception_fp_ieee_overflow 0
		.amdhsa_exception_fp_ieee_underflow 0
		.amdhsa_exception_fp_ieee_inexact 0
		.amdhsa_exception_int_div_zero 0
	.end_amdhsa_kernel

; __global__ void __launch_bounds__(NTHREADS, 2) fwd_kernel(Args args) {
amdhsa.kernels:
  - .agpr_count:     0
    .args:
      - .offset:         0
        .size:           280
        .value_kind:     by_value
      - .offset:         280
        .size:           4
        .value_kind:     hidden_block_count_x
      - .offset:         284
        .size:           4
        .value_kind:     hidden_block_count_y
      - .offset:         288
        .size:           4
        .value_kind:     hidden_block_count_z
      - .offset:         292
        .size:           2
        .value_kind:     hidden_group_size_x
      - .offset:         294
        .size:           2
        .value_kind:     hidden_group_size_y
      - .offset:         296
        .size:           2
        .value_kind:     hidden_group_size_z
      - .offset:         298
        .size:           2
        .value_kind:     hidden_remainder_x
      - .offset:         300
        .size:           2
        .value_kind:     hidden_remainder_y
      - .offset:         302
        .size:           2
        .value_kind:     hidden_remainder_z
      - .offset:         320
        .size:           8
        .value_kind:     hidden_global_offset_x
      - .offset:         328
        .size:           8
        .value_kind:     hidden_global_offset_y
      - .offset:         336
        .size:           8
        .value_kind:     hidden_global_offset_z
      - .offset:         344
        .size:           2
        .value_kind:     hidden_grid_dims
      - .offset:         368
        .size:           8
        .value_kind:     hidden_multigrid_sync_arg
      - .offset:         400
        .size:           4
        .value_kind:     hidden_dynamic_lds_size
    .group_segment_fixed_size: 0
    .kernarg_segment_align: 8
    .kernarg_segment_size: 536
    .language:       OpenCL C
    .language_version:
      - 2
      - 0
    .max_flat_workgroup_size: 512
    .name:           _Z10fwd_kernel4Args
    .private_segment_fixed_size: 0
    .sgpr_count:     108
    .sgpr_spill_count: 11
    .symbol:         _Z10fwd_kernel4Args.kd
    .uniform_work_group_size: 1
    .uses_dynamic_stack: false
    .vgpr_count:     256
    .vgpr_spill_count: 0
    .wavefront_size: 64
